# SwiGLU epilogue: rstd LDS-read wait sunk below independent address math (on top of final-norm nt loads)
# baseline (speedup 1.0000x reference)
; #define LAS __attribute__((address_space(3)))
; __device__ __forceinline__ void rs_read(LAS unsigned char* lds, int buf, int wr, int fr, float (&rs)[2][4]) {
;     const LAS float* t = (const LAS float*)(lds + RS_LDS_OFF) + buf * 256 + wr * 64 + fr;
; #pragma unroll
;     for (int ai = 0; ai < 2; ++ai)
; #pragma unroll
;         for (int m = 0; m < 4; ++m) rs[ai][m] = t[ai * 128 + m * 16];
; }
;     __device__ __forceinline__ void rs_first(const Unit& u, LAS unsigned char* lds, int tid) const { f32x4 a, b; rs_issue(ssp, u, tid, a, b); rs_finish(lds, 0, tid, a, b); }
;     __device__ __forceinline__ void operator()(const f32x4 (&acc)[2][2][4][2], const Unit& u, int wr, int wc, int fr, int fq, LAS unsigned char* lds, int tid, int ui, const Unit& nxt, bool has_next) const {
;         f32x4 na, nb; if (has_next) rs_issue(ssp, nxt, tid, na, nb);
;         const int row0 = u.pm * 256 + wr * 64 + fr, col0 = u.pn * 128 + wc * 32 + 8 * fq;
;         float rsv[2][4]; rs_read(lds, ui & 1, wr, fr, rsv);
; #pragma unroll
;         for (int ai = 0; ai < 2; ++ai)
; #pragma unroll
;             for (int m = 0; m < 4; ++m) {
;                 const int row = row0 + ai * 128 + m * 16;
;                 const float rs = rsv[ai][m];
;                 typedef float f32x2 __attribute__((ext_vector_type(2)));
;                 const f32x2 rs2 = (f32x2){rs, rs}, nrs2 = (f32x2){-LOG2E * rs, -LOG2E * rs};
;                 unsigned wv[4];
; #pragma unroll
;                 for (int n = 0; n < 2; ++n)
; #pragma unroll
;                     for (int hp = 0; hp < 2; ++hp) {
;                         const f32x2 ag = (f32x2){acc[ai][0][m][n][2 * hp], acc[ai][0][m][n][2 * hp + 1]}, au = (f32x2){acc[ai][1][m][n][2 * hp], acc[ai][1][m][n][2 * hp + 1]};
;                         const f32x2 g = ag * rs2, up = au * rs2, ne = ag * nrs2;
;                         const f32x2 dd = (f32x2){__builtin_amdgcn_exp2f(ne.x), __builtin_amdgcn_exp2f(ne.y)} + 1.0f;
;                         const f32x2 rr = (f32x2){__builtin_amdgcn_rcpf(dd.x), __builtin_amdgcn_rcpf(dd.y)};
;                         const f32x2 oo = (g * rr) * up;
;                         wv[n * 2 + hp] = cvt_pk_bf16(oo.x, oo.y);
;                     }
;                 u32x4 w; w.x = wv[0]; w.y = wv[1]; w.z = wv[2]; w.w = wv[3];
;                 __builtin_nontemporal_store(w, (u32x4*)(O + (size_t)row * FF + col0));
.LBB0_241:
	s_lshl_b32 s4, s58, 10
	s_and_b32 s25, s4, 0x400
	v_add_u32_e32 v148, s25, v163
	ds_read2_b32 v[156:157], v148 offset1:16
	ds_read2_b32 v[152:153], v148 offset0:32 offset1:48
	ds_read2_b32 v[150:151], v148 offset0:128 offset1:144
	ds_read2_b32 v[148:149], v148 offset0:160 offset1:176
	v_lshl_or_b32 v154, s30, 7, v164
	v_lshl_add_u32 v166, s28, 8, v160
	v_ashrrev_i32_e32 v155, 31, v154
	v_mov_b64_e32 v[186:187], s[16:17]
	v_lshlrev_b64 v[188:189], 1, v[154:155]
	v_add_u32_e32 v167, 0, v166
	v_mad_i64_i32 v[174:175], s[4:5], v167, s6, v[186:187]
	v_lshl_add_u64 v[174:175], v[174:175], 0, v[188:189]
	v_pk_mul_f32 v[128:129], v[132:133], v[128:129]
	s_waitcnt lgkmcnt(0)
	v_mul_f32_e32 v170, 0xbfb8aa3b, v156
	v_mul_f32_e32 v172, v156, v156
	v_rcp_f32_e32 v172, v172
	v_pk_mul_f32 v[132:133], v[132:133], v[170:171] op_sel_hi:[1,0]
	v_pk_mul_f32 v[130:131], v[134:135], v[130:131]
	v_pk_mul_f32 v[134:135], v[134:135], v[170:171] op_sel_hi:[1,0]
	v_exp_f32_e32 v132, v132
	v_exp_f32_e32 v133, v133
	v_exp_f32_e32 v134, v134
	v_exp_f32_e32 v135, v135
	v_pk_fma_f32 v[132:133], v[132:133], v[172:173], v[172:173] op_sel_hi:[1,0,0]
	v_pk_fma_f32 v[134:135], v[134:135], v[172:173], v[172:173] op_sel_hi:[1,0,0]
	v_rcp_f32_e32 v132, v132
	v_rcp_f32_e32 v133, v133
	v_rcp_f32_e32 v134, v134
	v_rcp_f32_e32 v135, v135
	v_pk_mul_f32 v[128:129], v[128:129], v[132:133]
	v_pk_mul_f32 v[130:131], v[130:131], v[134:135]
	v_cvt_pk_bf16_f32 v132, v128, v129
	v_cvt_pk_bf16_f32 v133, v130, v131
	v_pk_mul_f32 v[120:121], v[124:125], v[120:121]
	v_pk_mul_f32 v[124:125], v[124:125], v[170:171] op_sel_hi:[1,0]
	v_pk_mul_f32 v[122:123], v[126:127], v[122:123]
	v_pk_mul_f32 v[126:127], v[126:127], v[170:171] op_sel_hi:[1,0]
	v_exp_f32_e32 v124, v124
	v_exp_f32_e32 v125, v125
	v_exp_f32_e32 v126, v126
	v_exp_f32_e32 v127, v127
	v_pk_fma_f32 v[124:125], v[124:125], v[172:173], v[172:173] op_sel_hi:[1,0,0]
	v_pk_fma_f32 v[126:127], v[126:127], v[172:173], v[172:173] op_sel_hi:[1,0,0]
	v_rcp_f32_e32 v124, v124
	v_rcp_f32_e32 v125, v125
	v_rcp_f32_e32 v126, v126
	v_rcp_f32_e32 v127, v127
	v_pk_mul_f32 v[120:121], v[120:121], v[124:125]
	v_pk_mul_f32 v[122:123], v[122:123], v[126:127]
	v_cvt_pk_bf16_f32 v134, v120, v121
	v_cvt_pk_bf16_f32 v135, v122, v123
	global_store_dwordx4 v[174:175], v[132:135], off
	s_cmp_eq_u64 s[22:23], 0
	s_cbranch_scc1 .Lmy_epibar_swiglu
	s_barrier
